# p2 row items: first-half 15-load batch also issued at item entry (first half = one round trip)
# baseline (speedup 1.0000x reference)
; DEVI void mixab_row4(const Params& P, int l, int base, int lt0, int tid) {
;     ...
;   const bfu* z = (const bfu*)(P.ws + O_Z);
;   const int c = tid * 4;
;   {
;     float pk[6][4], ab[4][4], wa[3][4];
; #pragma unroll
;     for (int k = 0; k < 6; ++k) {
;       const int tt = t0 - 2 + k;
;       if (tt >= 0) {
;         const bfu* zr = z + (long)(lt0 - 2 + k) * NCOL;
;         float ac[4], ax[4];
;         load4bf(zr + 1024 + c, ac); load4bf(zr + 2048 + c, ax);
; #pragma unroll
;         for (int i = 0; i < 4; ++i) pk[k][i] = ac[i] * ax[i];
;       } else if (ti.sample) {
;         ld4f(P.in[2] + ((long)(l * 8 + ti.seq) * 2 + (tt + 2)) * 1024 + c, pk[k]);
;       } else {
; #pragma unroll
;         for (int i = 0; i < 4; ++i) pk[k][i] = 0.f;
;       }
;     }
; #pragma unroll
;     for (int r = 0; r < 4; ++r) load4bf(z + (long)(lt0 + r) * NCOL + c, ab[r]);
; #pragma unroll
;     for (int k = 0; k < 3; ++k) ld4f(P.in[8] + (long)(l * 3 + k) * 1024 + c, wa[k]);
.LBB0_351:
	s_add_i32 s74, s48, -2
	v_lshlrev_b64 v[178:179], 1, v[100:101]
	v_mad_i64_i32 v[180:181], s[42:43], s74, v191, v[74:75]
	s_add_i32 vcc_lo, s48, -1
	v_lshl_add_u64 v[180:181], v[180:181], 0, v[178:179]
	v_mad_i64_i32 v[182:183], s[42:43], vcc_lo, v191, v[74:75]
	s_add_i32 vcc_lo, s48, -3
	v_lshl_add_u64 v[182:183], v[182:183], 0, v[178:179]
	v_mad_i64_i32 v[196:197], s[42:43], vcc_lo, v191, v[74:75]
	global_load_dwordx2 v[210:211], v[180:181], off offset:2048
	global_load_dwordx2 v[214:215], v[182:183], off offset:2048
	s_mov_b64 s[42:43], 0x1000
	v_lshl_add_u64 v[196:197], v[196:197], 0, v[178:179]
	v_lshl_add_u64 v[180:181], v[180:181], 0, s[42:43]
	v_lshl_add_u64 v[182:183], v[182:183], 0, s[42:43]
	v_lshl_add_u64 v[196:197], v[196:197], 0, s[42:43]
	global_load_dwordx2 v[208:209], v[180:181], off
	global_load_dwordx2 v[212:213], v[182:183], off
	global_load_dwordx2 v[218:219], v[180:181], off offset:2048
	global_load_dwordx2 v[220:221], v[182:183], off offset:2048
	global_load_dwordx2 v[216:217], v[196:197], off offset:2048
	v_mad_i64_i32 v[198:199], s[52:53], s48, v191, v[74:75]
	v_lshl_add_u64 v[198:199], v[198:199], 0, v[104:105]
	s_or_b32 s52, s48, 1
	s_or_b32 s60, s48, 2
	s_or_b32 s62, s48, 3
	v_mad_i64_i32 v[202:203], s[56:57], s52, v191, v[74:75]
	global_load_dwordx2 v[226:227], v[198:199], off offset:2048
	v_lshl_add_u64 v[204:205], v[198:199], 0, s[42:43]
	v_lshl_add_u64 v[202:203], v[202:203], 0, v[104:105]
	global_load_dwordx2 v[228:229], v[204:205], off
	global_load_dwordx2 v[12:13], v[202:203], off offset:2048
	v_lshl_add_u64 v[16:17], v[202:203], 0, s[42:43]
	v_mad_i64_i32 v[202:203], s[56:57], s60, v191, v[74:75]
	v_mad_i64_i32 v[18:19], s[56:57], s62, v191, v[74:75]
	v_lshl_add_u64 v[202:203], v[202:203], 0, v[104:105]
	v_lshl_add_u64 v[20:21], v[18:19], 0, v[104:105]
	v_lshl_add_u64 v[18:19], v[202:203], 0, s[42:43]
	global_load_dwordx2 v[14:15], v[202:203], off offset:2048
	global_load_dwordx2 v[38:39], v[20:21], off offset:2048
	global_load_dwordx2 v[40:41], v[16:17], off
	v_lshl_add_u64 v[20:21], v[20:21], 0, s[42:43]
	v_mad_i64_i32 v[26:27], s[56:57], s62, v191, v[106:107]
	global_load_dwordx2 v[230:231], v[18:19], off
	global_load_dwordx2 v[42:43], v[20:21], off
	global_load_dwordx2 v[44:45], v[26:27], off
	v_mad_i64_i32 v[26:27], s[56:57], s60, v191, v[106:107]
	global_load_dwordx2 v[46:47], v[26:27], off
	v_mad_i64_i32 v[26:27], s[56:57], s52, v191, v[106:107]
	v_mad_i64_i32 v[34:35], s[56:57], s48, v191, v[106:107]
	global_load_dwordx2 v[48:49], v[26:27], off
	s_nop 0
	global_load_dwordx4 v[26:29], v[108:109], off
	global_load_dwordx4 v[30:33], v[112:113], off
	global_load_dwordx2 v[50:51], v[34:35], off
	s_nop 0
	global_load_dwordx4 v[34:37], v[110:111], off
	s_cmp_lg_u32 s64, 0
	s_cselect_b64 s[50:51], -1, 0
	s_cmp_eq_u32 s64, 0
	s_mov_b64 s[42:43], -1
	s_cbranch_scc1 .LBB0_353
	s_mov_b64 s[42:43], 0
	s_waitcnt vmcnt(0)
	v_mov_b32_e32 v2, v208
	v_mov_b32_e32 v3, v209
	v_mov_b32_e32 v0, v210
	v_mov_b32_e32 v1, v211
	v_lshlrev_b32_e32 v5, 16, v3
	v_lshlrev_b32_e32 v4, 16, v2
	v_and_b32_e32 v3, 0xffff0000, v3
	v_and_b32_e32 v2, 0xffff0000, v2
	v_and_b32_e32 v7, 0xffff0000, v1
	v_and_b32_e32 v6, 0xffff0000, v0
	v_lshlrev_b32_e32 v1, 16, v1
	v_lshlrev_b32_e32 v0, 16, v0
	v_pk_mul_f32 v[22:23], v[0:1], v[4:5]
	v_pk_mul_f32 v[2:3], v[6:7], v[2:3]

; DEVI void mixab_row4(const Params& P, int l, int base, int lt0, int tid) {
;     ...
; #pragma unroll
;     for (int r = 0; r < 4; ++r) load4bf(z + (long)(lt0 + r) * NCOL + c, ab[r]);
; #pragma unroll
;     for (int k = 0; k < 3; ++k) ld4f(P.in[8] + (long)(l * 3 + k) * 1024 + c, wa[k]);
; #pragma unroll
;     for (int r = 0; r < 4; ++r) {
;       float o[4];
; #pragma unroll
;       for (int i = 0; i < 4; ++i) o[i] = ab[r][i] * (wa[0][i] * pk[r][i] + wa[1][i] * pk[r + 1][i] + wa[2][i] * pk[r + 2][i]);
;       store4bf((bfu*)(P.ws + O_UA) + (long)(lt0 + r) * 1024 + c, o);
;     }
.LBB0_361:
	v_mad_i64_i32 v[0:1], s[52:53], s48, v191, v[74:75]
	v_lshl_add_u64 v[0:1], v[0:1], 0, v[104:105]
	s_movk_i32 s4, 0x1000
	s_or_b32 s52, s48, 1
	s_or_b32 s60, s48, 2
	s_or_b32 s62, s48, 3
	s_waitcnt vmcnt(0)
	v_mov_b32_e32 v10, v226
	v_mov_b32_e32 v11, v227
	v_mov_b32_e32 v4, v228
	v_mov_b32_e32 v5, v229
	v_mov_b32_e32 v8, v230
	v_mov_b32_e32 v9, v231
	s_ashr_i32 s49, s48, 31
	s_lshl_b64 s[56:57], s[48:49], 11
	s_ashr_i32 s53, s52, 31
	s_lshl_b64 s[58:59], s[52:53], 11
	s_ashr_i32 s61, s60, 31
	s_lshl_b64 s[60:61], s[60:61], 11
	s_ashr_i32 s63, s62, 31
	s_lshl_b64 s[62:63], s[62:63], 11
	s_and_b64 s[52:53], s[26:27], exec
	s_cselect_b32 s47, 0xffc, 28
	s_cmp_eq_u32 s64, s47
	s_cselect_b64 s[52:53], -1, 0
	s_cmp_lg_u32 s64, s47
	v_lshlrev_b32_e32 v52, 16, v10
	v_lshlrev_b32_e32 v53, 16, v11
	v_lshlrev_b32_e32 v58, 16, v12
	v_lshlrev_b32_e32 v59, 16, v13
	v_lshlrev_b32_e32 v56, 16, v4
	v_lshlrev_b32_e32 v57, 16, v5
	v_and_b32_e32 v55, 0xffff0000, v11
	v_and_b32_e32 v54, 0xffff0000, v10
	v_and_b32_e32 v5, 0xffff0000, v5
	v_and_b32_e32 v4, 0xffff0000, v4
	v_pk_mul_f32 v[52:53], v[52:53], v[56:57]
	v_pk_mul_f32 v[4:5], v[54:55], v[4:5]
	v_and_b32_e32 v61, 0xffff0000, v13
	v_and_b32_e32 v60, 0xffff0000, v12
	v_lshlrev_b32_e32 v10, 16, v14
	v_and_b32_e32 v11, 0xffff0000, v14
	v_lshlrev_b32_e32 v12, 16, v15
	v_lshlrev_b32_e32 v62, 16, v40
	v_lshlrev_b32_e32 v63, 16, v41
	v_pk_mul_f32 v[58:59], v[58:59], v[62:63]
	v_and_b32_e32 v13, 0xffff0000, v15
	v_lshlrev_b32_e32 v14, 16, v38
	v_and_b32_e32 v15, 0xffff0000, v38
	v_lshlrev_b32_e32 v38, 16, v39
	v_lshlrev_b32_e32 v170, 16, v8
	v_and_b32_e32 v171, 0xffff0000, v8
	v_lshlrev_b32_e32 v172, 16, v9
	v_and_b32_e32 v173, 0xffff0000, v9
	v_pk_mul_f32 v[8:9], v[10:11], v[170:171]
	v_pk_mul_f32 v[10:11], v[12:13], v[172:173]
	v_and_b32_e32 v39, 0xffff0000, v39
	v_lshlrev_b32_e32 v12, 16, v42
	v_and_b32_e32 v13, 0xffff0000, v42
	v_mov_b32_e32 v62, v26
	v_mov_b32_e32 v63, v28
	v_mov_b32_e32 v174, v30
	v_mov_b32_e32 v175, v32
	v_mov_b32_e32 v28, v27
	v_mov_b32_e32 v32, v31
	v_lshlrev_b32_e32 v27, 16, v51
	v_lshlrev_b32_e32 v26, 16, v50
	v_and_b32_e32 v31, 0xffff0000, v51
	v_and_b32_e32 v30, 0xffff0000, v50
	v_mov_b32_e32 v50, v34
	v_mov_b32_e32 v51, v36
	v_pk_mul_f32 v[176:177], v[24:25], v[50:51]
	v_mov_b32_e32 v36, v35
	v_pk_fma_f32 v[22:23], v[22:23], v[62:63], v[176:177]
	v_pk_mul_f32 v[34:35], v[6:7], v[36:37]
	v_pk_fma_f32 v[22:23], v[52:53], v[174:175], v[22:23]
	v_pk_fma_f32 v[2:3], v[2:3], v[28:29], v[34:35]
	v_pk_mul_f32 v[22:23], v[22:23], v[26:27]
	v_pk_fma_f32 v[2:3], v[4:5], v[32:33], v[2:3]
	v_and_b32_sdwa v26, v23, v95 dst_sel:DWORD dst_unused:UNUSED_PAD src0_sel:WORD_1 src1_sel:DWORD
	v_pk_mul_f32 v[2:3], v[2:3], v[30:31]
	v_and_b32_sdwa v27, v22, v95 dst_sel:DWORD dst_unused:UNUSED_PAD src0_sel:WORD_1 src1_sel:DWORD
	v_add3_u32 v22, v22, v27, s39
	v_add3_u32 v23, v23, v26, s39
	v_and_b32_sdwa v26, v3, v95 dst_sel:DWORD dst_unused:UNUSED_PAD src0_sel:WORD_1 src1_sel:DWORD
	v_and_b32_sdwa v27, v2, v95 dst_sel:DWORD dst_unused:UNUSED_PAD src0_sel:WORD_1 src1_sel:DWORD
	v_add3_u32 v3, v3, v26, s39
	v_add3_u32 v2, v2, v27, s39
	v_lshlrev_b32_e32 v42, 16, v43
	v_and_b32_e32 v43, 0xffff0000, v43
	v_and_b32_e32 v3, 0xffff0000, v3
	v_and_b32_e32 v2, 0xffff0000, v2
	v_pk_mul_f32 v[12:13], v[14:15], v[12:13]
	v_pk_mul_f32 v[14:15], v[38:39], v[42:43]
	v_lshl_add_u64 v[38:39], v[114:115], 0, s[56:57]
	v_or_b32_sdwa v3, v3, v23 dst_sel:DWORD dst_unused:UNUSED_PAD src0_sel:DWORD src1_sel:WORD_1
	v_or_b32_sdwa v2, v2, v22 dst_sel:DWORD dst_unused:UNUSED_PAD src0_sel:DWORD src1_sel:WORD_1
	global_store_dwordx2 v[38:39], v[2:3], off
	v_pk_mul_f32 v[2:3], v[52:53], v[50:51]
	v_and_b32_e32 v41, 0xffff0000, v41
	v_and_b32_e32 v40, 0xffff0000, v40
	v_pk_fma_f32 v[2:3], v[24:25], v[62:63], v[2:3]
	v_pk_mul_f32 v[22:23], v[4:5], v[36:37]
	v_pk_mul_f32 v[40:41], v[60:61], v[40:41]
	v_lshlrev_b32_e32 v57, 16, v49
	v_lshlrev_b32_e32 v56, 16, v48
	v_pk_fma_f32 v[2:3], v[58:59], v[174:175], v[2:3]
	v_pk_fma_f32 v[6:7], v[6:7], v[28:29], v[22:23]
	v_and_b32_e32 v49, 0xffff0000, v49
; DEVI void mixab_row4(const Params& P, int l, int base, int lt0, int tid) {
;     ...
; #pragma unroll
;     for (int r = 0; r < 4; ++r) {
;       float o[4];
; #pragma unroll
;       for (int i = 0; i < 4; ++i) o[i] = ab[r][i] * (wa[0][i] * pk[r][i] + wa[1][i] * pk[r + 1][i] + wa[2][i] * pk[r + 2][i]);
;       store4bf((bfu*)(P.ws + O_UA) + (long)(lt0 + r) * 1024 + c, o);
;     }
;     if (t0 + 4 == T) {
;       float* ca = ti.sample ? P.out + OUT_CAS + (long)(l * 8 + ti.seq) * 2 * 1024 + c : P.out + OUT_CAP + (long)(l * 4 + ti.seq) * 2 * 1024 + c;
; #pragma unroll
;       for (int r = 0; r < 2; ++r)
;         *reinterpret_cast<float4*>(ca + r * 1024) = make_float4(pk[r + 4][0], pk[r + 4][1], pk[r + 4][2], pk[r + 4][3]);
;     }
	v_and_b32_e32 v48, 0xffff0000, v48
	v_pk_mul_f32 v[2:3], v[2:3], v[56:57]
	v_pk_fma_f32 v[6:7], v[40:41], v[32:33], v[6:7]
	v_and_b32_sdwa v22, v3, v95 dst_sel:DWORD dst_unused:UNUSED_PAD src0_sel:WORD_1 src1_sel:DWORD
	v_pk_mul_f32 v[6:7], v[6:7], v[48:49]
	v_and_b32_sdwa v23, v2, v95 dst_sel:DWORD dst_unused:UNUSED_PAD src0_sel:WORD_1 src1_sel:DWORD
	v_add3_u32 v2, v2, v23, s39
	v_add3_u32 v3, v3, v22, s39
	v_and_b32_sdwa v22, v7, v95 dst_sel:DWORD dst_unused:UNUSED_PAD src0_sel:WORD_1 src1_sel:DWORD
	v_and_b32_sdwa v23, v6, v95 dst_sel:DWORD dst_unused:UNUSED_PAD src0_sel:WORD_1 src1_sel:DWORD
	v_add3_u32 v7, v7, v22, s39
	v_add3_u32 v6, v6, v23, s39
	v_and_b32_e32 v7, 0xffff0000, v7
	v_and_b32_e32 v6, 0xffff0000, v6
	v_lshl_add_u64 v[42:43], v[114:115], 0, s[58:59]
	v_or_b32_sdwa v3, v7, v3 dst_sel:DWORD dst_unused:UNUSED_PAD src0_sel:DWORD src1_sel:WORD_1
	v_or_b32_sdwa v2, v6, v2 dst_sel:DWORD dst_unused:UNUSED_PAD src0_sel:DWORD src1_sel:WORD_1
	global_store_dwordx2 v[42:43], v[2:3], off
	v_pk_mul_f32 v[2:3], v[58:59], v[50:51]
	v_mov_b32_e32 v6, v8
	v_pk_fma_f32 v[2:3], v[52:53], v[62:63], v[2:3]
	v_mov_b32_e32 v7, v10
	v_pk_mul_f32 v[22:23], v[40:41], v[36:37]
	v_lshlrev_b32_e32 v55, 16, v47
	v_lshlrev_b32_e32 v54, 16, v46
	v_pk_fma_f32 v[2:3], v[6:7], v[174:175], v[2:3]
	v_pk_fma_f32 v[4:5], v[4:5], v[28:29], v[22:23]
	v_mov_b32_e32 v22, v9
	v_mov_b32_e32 v23, v11
	v_and_b32_e32 v47, 0xffff0000, v47
	v_and_b32_e32 v46, 0xffff0000, v46
	v_pk_mul_f32 v[2:3], v[2:3], v[54:55]
	v_pk_fma_f32 v[4:5], v[22:23], v[32:33], v[4:5]
	v_and_b32_sdwa v24, v3, v95 dst_sel:DWORD dst_unused:UNUSED_PAD src0_sel:WORD_1 src1_sel:DWORD
	v_pk_mul_f32 v[4:5], v[4:5], v[46:47]
	v_and_b32_sdwa v25, v2, v95 dst_sel:DWORD dst_unused:UNUSED_PAD src0_sel:WORD_1 src1_sel:DWORD
	v_add3_u32 v2, v2, v25, s39
	v_add3_u32 v3, v3, v24, s39
	v_and_b32_sdwa v24, v5, v95 dst_sel:DWORD dst_unused:UNUSED_PAD src0_sel:WORD_1 src1_sel:DWORD
	v_and_b32_sdwa v25, v4, v95 dst_sel:DWORD dst_unused:UNUSED_PAD src0_sel:WORD_1 src1_sel:DWORD
	v_add3_u32 v5, v5, v24, s39
	v_add3_u32 v4, v4, v25, s39
	v_and_b32_e32 v5, 0xffff0000, v5
	v_and_b32_e32 v4, 0xffff0000, v4
	v_lshl_add_u64 v[170:171], v[114:115], 0, s[60:61]
	v_or_b32_sdwa v3, v5, v3 dst_sel:DWORD dst_unused:UNUSED_PAD src0_sel:DWORD src1_sel:WORD_1
	v_or_b32_sdwa v2, v4, v2 dst_sel:DWORD dst_unused:UNUSED_PAD src0_sel:DWORD src1_sel:WORD_1
	global_store_dwordx2 v[170:171], v[2:3], off
	v_pk_mul_f32 v[2:3], v[6:7], v[50:51]
	v_mov_b32_e32 v4, v12
	v_pk_fma_f32 v[2:3], v[58:59], v[62:63], v[2:3]
	v_mov_b32_e32 v5, v14
	v_pk_fma_f32 v[2:3], v[4:5], v[174:175], v[2:3]
	v_pk_mul_f32 v[4:5], v[22:23], v[36:37]
	v_lshlrev_b32_e32 v61, 16, v45
	v_lshlrev_b32_e32 v60, 16, v44
	v_pk_fma_f32 v[4:5], v[40:41], v[28:29], v[4:5]
	v_mov_b32_e32 v6, v13
	v_mov_b32_e32 v7, v15
	v_and_b32_e32 v45, 0xffff0000, v45
	v_and_b32_e32 v44, 0xffff0000, v44
	v_pk_mul_f32 v[2:3], v[2:3], v[60:61]
	v_pk_fma_f32 v[4:5], v[6:7], v[32:33], v[4:5]
	v_and_b32_sdwa v6, v3, v95 dst_sel:DWORD dst_unused:UNUSED_PAD src0_sel:WORD_1 src1_sel:DWORD
	v_pk_mul_f32 v[4:5], v[4:5], v[44:45]
	v_and_b32_sdwa v7, v2, v95 dst_sel:DWORD dst_unused:UNUSED_PAD src0_sel:WORD_1 src1_sel:DWORD
	v_add3_u32 v2, v2, v7, s39
	v_add3_u32 v3, v3, v6, s39
	v_and_b32_sdwa v6, v5, v95 dst_sel:DWORD dst_unused:UNUSED_PAD src0_sel:WORD_1 src1_sel:DWORD
	v_and_b32_sdwa v7, v4, v95 dst_sel:DWORD dst_unused:UNUSED_PAD src0_sel:WORD_1 src1_sel:DWORD
	v_add3_u32 v5, v5, v6, s39
	v_add3_u32 v4, v4, v7, s39
	v_and_b32_e32 v5, 0xffff0000, v5
	v_and_b32_e32 v4, 0xffff0000, v4
	v_lshl_add_u64 v[172:173], v[114:115], 0, s[62:63]
	v_or_b32_sdwa v3, v5, v3 dst_sel:DWORD dst_unused:UNUSED_PAD src0_sel:DWORD src1_sel:WORD_1
	v_or_b32_sdwa v2, v4, v2 dst_sel:DWORD dst_unused:UNUSED_PAD src0_sel:DWORD src1_sel:WORD_1
	global_store_dwordx2 v[172:173], v[2:3], off
	s_cbranch_scc1 .LBB0_367
	s_and_b64 vcc, exec, s[42:43]
	s_mov_b64 s[66:67], -1
	s_cbranch_vccnz .LBB0_364
	v_readlane_b32 s4, v254, 62
	s_add_u32 s64, s4, s54
	v_readlane_b32 s4, v254, 63
	s_addc_u32 s65, s4, s55
	s_mov_b64 s[66:67], 0
